# c16 plus scalar-base addressing for the attention K/V tile-stream loads (no 64-bit VALU address adds in the vector sections)
# speedup vs baseline: 1.0240x; 1.0038x over previous
.LBB0_676:
	global_load_dwordx4 v[100:103], v162, s[2:3]
	global_load_dwordx4 v[104:107], v166, s[2:3]
	global_load_dwordx4 v[108:111], v162, s[4:5]
	global_load_dwordx4 v[96:99], v166, s[4:5]
	s_add_i32 s89, s89, 2
	s_branch .LBB0_678

.LBB0_687:
	global_load_dwordx4 v[100:103], v162, s[2:3]
	global_load_dwordx4 v[104:107], v166, s[2:3]
	global_load_dwordx4 v[108:111], v162, s[4:5]
	global_load_dwordx4 v[96:99], v166, s[4:5]

.LBB0_699:
	global_load_dwordx4 v[100:103], v162, s[70:71]
	global_load_dwordx4 v[104:107], v166, s[70:71]
	global_load_dwordx4 v[108:111], v162, s[2:3]
	global_load_dwordx4 v[96:99], v166, s[2:3]

.LBB0_741:
	global_load_dwordx4 v[100:103], v162, s[4:5]
	global_load_dwordx4 v[104:107], v166, s[4:5]
	global_load_dwordx4 v[108:111], v162, s[6:7]
	global_load_dwordx4 v[96:99], v166, s[6:7]
	s_add_i32 s80, s80, 2
	s_branch .LBB0_743

.LBB0_752:
	global_load_dwordx4 v[100:103], v162, s[4:5]
	global_load_dwordx4 v[104:107], v166, s[4:5]
	global_load_dwordx4 v[108:111], v162, s[6:7]
	global_load_dwordx4 v[96:99], v166, s[6:7]

.LBB0_764:
	global_load_dwordx4 v[100:103], v162, s[72:73]
	global_load_dwordx4 v[104:107], v166, s[72:73]
	global_load_dwordx4 v[108:111], v162, s[4:5]
	global_load_dwordx4 v[96:99], v166, s[4:5]

.LBB0_1336:
	global_load_dwordx4 v[100:103], v164, s[0:1]
	global_load_dwordx4 v[104:107], v166, s[0:1]
	global_load_dwordx4 v[112:115], v164, s[2:3]
	global_load_dwordx4 v[108:111], v166, s[2:3]
	s_waitcnt lgkmcnt(0)
	s_barrier
	s_setprio 1
	ds_read_b128 v[64:67], v194
	ds_read_b128 v[68:71], v194 offset:32
	ds_read_b128 v[72:75], v194 offset:64
	ds_read_b128 v[76:79], v194 offset:96
	ds_read_b128 v[196:199], v194 offset:128
	ds_read_b128 v[200:203], v194 offset:160
	ds_read_b128 v[204:207], v194 offset:192
	ds_read_b128 v[208:211], v194 offset:224
	s_waitcnt lgkmcnt(4)
	v_pk_add_f32 v[94:95], v[78:79], v[180:181] op_sel:[0,1] op_sel_hi:[1,1] neg_lo:[0,1] neg_hi:[0,1]
	v_pk_add_f32 v[92:93], v[76:77], v[180:181] op_sel:[0,1] op_sel_hi:[1,1] neg_lo:[0,1] neg_hi:[0,1]
	v_pk_add_f32 v[90:91], v[74:75], v[180:181] op_sel:[0,1] op_sel_hi:[1,1] neg_lo:[0,1] neg_hi:[0,1]
	v_pk_add_f32 v[88:89], v[72:73], v[180:181] op_sel:[0,1] op_sel_hi:[1,1] neg_lo:[0,1] neg_hi:[0,1]
	v_pk_add_f32 v[86:87], v[70:71], v[180:181] op_sel:[0,1] op_sel_hi:[1,1] neg_lo:[0,1] neg_hi:[0,1]
	v_pk_add_f32 v[84:85], v[68:69], v[180:181] op_sel:[0,1] op_sel_hi:[1,1] neg_lo:[0,1] neg_hi:[0,1]
	v_pk_add_f32 v[82:83], v[66:67], v[180:181] op_sel:[0,1] op_sel_hi:[1,1] neg_lo:[0,1] neg_hi:[0,1]
	v_pk_add_f32 v[80:81], v[64:65], v[180:181] op_sel:[0,1] op_sel_hi:[1,1] neg_lo:[0,1] neg_hi:[0,1]
	s_waitcnt lgkmcnt(0)
	v_pk_add_f32 v[78:79], v[210:211], v[180:181] op_sel:[0,1] op_sel_hi:[1,1] neg_lo:[0,1] neg_hi:[0,1]
	v_pk_add_f32 v[76:77], v[208:209], v[180:181] op_sel:[0,1] op_sel_hi:[1,1] neg_lo:[0,1] neg_hi:[0,1]
	v_pk_add_f32 v[74:75], v[206:207], v[180:181] op_sel:[0,1] op_sel_hi:[1,1] neg_lo:[0,1] neg_hi:[0,1]
	v_pk_add_f32 v[72:73], v[204:205], v[180:181] op_sel:[0,1] op_sel_hi:[1,1] neg_lo:[0,1] neg_hi:[0,1]
	v_pk_add_f32 v[70:71], v[202:203], v[180:181] op_sel:[0,1] op_sel_hi:[1,1] neg_lo:[0,1] neg_hi:[0,1]
	v_pk_add_f32 v[68:69], v[200:201], v[180:181] op_sel:[0,1] op_sel_hi:[1,1] neg_lo:[0,1] neg_hi:[0,1]
	v_pk_add_f32 v[66:67], v[198:199], v[180:181] op_sel:[0,1] op_sel_hi:[1,1] neg_lo:[0,1] neg_hi:[0,1]
	v_pk_add_f32 v[64:65], v[196:197], v[180:181] op_sel:[0,1] op_sel_hi:[1,1] neg_lo:[0,1] neg_hi:[0,1]
	ds_read_b64_tr_b16 v[196:197], v179 offset:0x4000
	ds_read_b64_tr_b16 v[198:199], v179 offset:0x4800
	ds_read_b64_tr_b16 v[200:201], v179 offset:0x5000
	ds_read_b64_tr_b16 v[202:203], v179 offset:0x5800
	ds_read_b64_tr_b16 v[204:205], v179 offset:0x6000
	ds_read_b64_tr_b16 v[206:207], v179 offset:0x6800
	ds_read_b64_tr_b16 v[208:209], v179 offset:0x7000
	ds_read_b64_tr_b16 v[210:211], v179 offset:0x7800
	ds_read_b64_tr_b16 v[212:213], v179 offset:0x4200
	ds_read_b64_tr_b16 v[214:215], v179 offset:0x4a00
	ds_read_b64_tr_b16 v[216:217], v179 offset:0x5200
	ds_read_b64_tr_b16 v[218:219], v179 offset:0x5a00
	ds_read_b64_tr_b16 v[220:221], v179 offset:0x6200
	ds_read_b64_tr_b16 v[222:223], v179 offset:0x6a00
	ds_read_b64_tr_b16 v[224:225], v179 offset:0x7200
	ds_read_b64_tr_b16 v[226:227], v179 offset:0x7a00
	s_waitcnt lgkmcnt(14)
	s_nop 0
	v_mfma_f32_32x32x16_bf16 v[0:15], v[160:163], v[196:199], v[0:15]
	ds_read_b64_tr_b16 v[196:197], v179 offset:0x4400
	ds_read_b64_tr_b16 v[198:199], v179 offset:0x4c00
	s_waitcnt lgkmcnt(14)
	v_mfma_f32_32x32x16_bf16 v[0:15], v[156:159], v[200:203], v[0:15]
	ds_read_b64_tr_b16 v[200:201], v179 offset:0x5400
	ds_read_b64_tr_b16 v[202:203], v179 offset:0x5c00
	s_waitcnt lgkmcnt(14)
	v_mfma_f32_32x32x16_bf16 v[0:15], v[152:155], v[204:207], v[0:15]
	ds_read_b64_tr_b16 v[204:205], v179 offset:0x6400
	ds_read_b64_tr_b16 v[206:207], v179 offset:0x6c00
	s_waitcnt lgkmcnt(14)
	v_mfma_f32_32x32x16_bf16 v[0:15], v[148:151], v[208:211], v[0:15]
	ds_read_b64_tr_b16 v[208:209], v179 offset:0x7400
	ds_read_b64_tr_b16 v[210:211], v179 offset:0x7c00
	s_waitcnt lgkmcnt(14)
	v_mfma_f32_32x32x16_bf16 v[48:63], v[160:163], v[212:215], v[48:63]
	ds_read_b64_tr_b16 v[212:213], v179 offset:0x4600
	ds_read_b64_tr_b16 v[214:215], v179 offset:0x4e00
	s_waitcnt lgkmcnt(14)
	v_mfma_f32_32x32x16_bf16 v[48:63], v[156:159], v[216:219], v[48:63]
	ds_read_b64_tr_b16 v[216:217], v179 offset:0x5600
	ds_read_b64_tr_b16 v[218:219], v179 offset:0x5e00
	s_waitcnt lgkmcnt(14)
	v_mfma_f32_32x32x16_bf16 v[48:63], v[152:155], v[220:223], v[48:63]
	ds_read_b64_tr_b16 v[220:221], v179 offset:0x6600
	ds_read_b64_tr_b16 v[222:223], v179 offset:0x6e00
	s_waitcnt lgkmcnt(14)
	v_mfma_f32_32x32x16_bf16 v[48:63], v[148:151], v[224:227], v[48:63]
	ds_read_b64_tr_b16 v[224:225], v179 offset:0x7600
	ds_read_b64_tr_b16 v[226:227], v179 offset:0x7e00
	s_waitcnt lgkmcnt(14)
	v_mfma_f32_32x32x16_bf16 v[32:47], v[160:163], v[196:199], v[32:47]
	ds_read_b128 v[196:199], v189 offset:0x8000
	s_waitcnt lgkmcnt(13)
	v_mfma_f32_32x32x16_bf16 v[32:47], v[156:159], v[200:203], v[32:47]
	ds_read_b128 v[200:203], v189 offset:0xa000
	s_waitcnt lgkmcnt(12)
	v_mfma_f32_32x32x16_bf16 v[32:47], v[152:155], v[204:207], v[32:47]
	ds_read_b128 v[204:207], v188 offset:0x8000
	s_waitcnt lgkmcnt(11)
	v_mfma_f32_32x32x16_bf16 v[32:47], v[148:151], v[208:211], v[32:47]
	ds_read_b128 v[208:211], v188 offset:0xa000
	s_waitcnt lgkmcnt(10)
	v_mfma_f32_32x32x16_bf16 v[16:31], v[160:163], v[212:215], v[16:31]
	ds_read_b128 v[160:163], v187 offset:0x8000
	s_waitcnt lgkmcnt(9)
	v_mfma_f32_32x32x16_bf16 v[16:31], v[156:159], v[216:219], v[16:31]
	ds_read_b128 v[156:159], v187 offset:0xa000
	s_waitcnt lgkmcnt(8)
	v_mfma_f32_32x32x16_bf16 v[16:31], v[152:155], v[220:223], v[16:31]
	ds_read_b128 v[152:155], v184 offset:0x8000
	s_waitcnt lgkmcnt(7)
	v_mfma_f32_32x32x16_bf16 v[16:31], v[148:151], v[224:227], v[16:31]
	ds_read_b128 v[148:151], v184 offset:0xa000
	s_waitcnt lgkmcnt(7)
	v_mfma_f32_32x32x16_bf16 v[80:95], v[196:199], v[144:147], v[80:95]
	ds_read_b128 v[196:199], v182 offset:0x8000
	s_waitcnt lgkmcnt(7)
	v_mfma_f32_32x32x16_bf16 v[64:79], v[200:203], v[144:147], v[64:79]
	ds_read_b128 v[200:203], v182 offset:0xa000
	s_waitcnt lgkmcnt(7)
	v_mfma_f32_32x32x16_bf16 v[80:95], v[204:207], v[136:139], v[80:95]
	ds_read_b128 v[204:207], v183 offset:0x8000
	s_waitcnt lgkmcnt(7)
	v_mfma_f32_32x32x16_bf16 v[64:79], v[208:211], v[136:139], v[64:79]
	ds_read_b128 v[208:211], v183 offset:0xa000
	s_waitcnt lgkmcnt(7)
	v_mfma_f32_32x32x16_bf16 v[80:95], v[160:163], v[128:131], v[80:95]
	ds_read_b128 v[160:163], v185 offset:0x8000
	s_waitcnt lgkmcnt(7)
	v_mfma_f32_32x32x16_bf16 v[64:79], v[156:159], v[128:131], v[64:79]
	ds_read_b128 v[156:159], v185 offset:0xa000
	s_waitcnt lgkmcnt(7)
	v_mfma_f32_32x32x16_bf16 v[80:95], v[152:155], v[124:127], v[80:95]
	ds_read_b128 v[152:155], v186 offset:0x8000
	s_waitcnt lgkmcnt(7)
	v_mfma_f32_32x32x16_bf16 v[64:79], v[148:151], v[124:127], v[64:79]
	ds_read_b128 v[148:151], v186 offset:0xa000
	s_waitcnt lgkmcnt(7)
	v_mfma_f32_32x32x16_bf16 v[80:95], v[196:199], v[120:123], v[80:95]
	s_waitcnt lgkmcnt(6)
	v_mfma_f32_32x32x16_bf16 v[64:79], v[200:203], v[120:123], v[64:79]
	s_waitcnt lgkmcnt(5)
	v_mfma_f32_32x32x16_bf16 v[80:95], v[204:207], v[116:119], v[80:95]
	s_waitcnt lgkmcnt(4)
	v_mfma_f32_32x32x16_bf16 v[64:79], v[208:211], v[116:119], v[64:79]
	s_waitcnt lgkmcnt(3)
	v_mfma_f32_32x32x16_bf16 v[80:95], v[160:163], v[140:143], v[80:95]
	s_waitcnt lgkmcnt(2)
	v_mfma_f32_32x32x16_bf16 v[64:79], v[156:159], v[140:143], v[64:79]
	s_waitcnt lgkmcnt(1)
	v_mfma_f32_32x32x16_bf16 v[80:95], v[152:155], v[132:135], v[80:95]
	s_waitcnt lgkmcnt(0)
	v_mfma_f32_32x32x16_bf16 v[64:79], v[148:151], v[132:135], v[64:79]
	s_setprio 0
	s_waitcnt lgkmcnt(0)
	s_barrier
	s_cmp_le_i32 s84, s78
	s_mov_b64 s[0:1], -1
	s_cbranch_scc0 .LBB0_1340
	s_add_i32 s0, s84, 63
	s_cmp_le_i32 s0, s75
	s_cbranch_scc1 .LBB0_1339
	v_cmp_gt_i32_e64 s[58:59], 26, v193
	v_cmp_gt_i32_e64 s[60:61], 27, v193
	v_cmp_gt_i32_e64 s[56:57], 25, v193
	v_cmp_gt_i32_e64 s[54:55], 24, v193
	v_cmp_gt_i32_e64 s[52:53], 19, v193
	v_cmp_gt_i32_e64 s[50:51], 18, v193
	v_cmp_gt_i32_e64 s[48:49], 17, v193
	v_cmp_gt_i32_e64 s[46:47], 16, v193
	v_cmp_gt_i32_e64 s[44:45], 11, v193
	v_cmp_gt_i32_e64 s[42:43], 10, v193
	v_cmp_gt_i32_e64 s[40:41], 9, v193
	v_cmp_gt_i32_e64 s[38:39], 8, v193
	v_cmp_gt_i32_e64 s[36:37], 3, v193
	v_cmp_gt_i32_e64 s[34:35], 2, v193
	v_cmp_gt_i32_e64 s[30:31], 1, v193
	v_cmp_gt_i32_e64 s[28:29], 0, v193
	v_cmp_gt_i32_e64 s[26:27], 58, v193
	v_cndmask_b32_e64 v80, v80, v169, s[28:29]
	v_cmp_gt_i32_e64 s[28:29], 59, v193
	v_cmp_gt_i32_e64 s[24:25], 57, v193
	v_cmp_gt_i32_e64 s[22:23], 56, v193
	v_cmp_gt_i32_e64 s[20:21], 51, v193
	v_cmp_gt_i32_e64 s[18:19], 50, v193
	v_cmp_gt_i32_e64 s[16:17], 49, v193
	v_cmp_gt_i32_e64 s[14:15], 48, v193
	v_cmp_gt_i32_e64 s[12:13], 43, v193
	v_cmp_gt_i32_e64 s[10:11], 42, v193
	v_cmp_gt_i32_e64 s[8:9], 41, v193
	v_cmp_gt_i32_e64 s[6:7], 40, v193
	v_cmp_gt_i32_e64 s[4:5], 35, v193
	v_cmp_gt_i32_e64 s[2:3], 34, v193
	v_cmp_gt_i32_e64 s[0:1], 33, v193
	v_cmp_gt_i32_e32 vcc, 32, v193
	v_cndmask_b32_e64 v95, v95, v169, s[60:61]
	v_cndmask_b32_e64 v94, v94, v169, s[58:59]
	v_cndmask_b32_e64 v93, v93, v169, s[56:57]
	v_cndmask_b32_e64 v92, v92, v169, s[54:55]
	v_cndmask_b32_e64 v91, v91, v169, s[52:53]
	v_cndmask_b32_e64 v90, v90, v169, s[50:51]
	v_cndmask_b32_e64 v89, v89, v169, s[48:49]
	v_cndmask_b32_e64 v88, v88, v169, s[46:47]
	v_cndmask_b32_e64 v87, v87, v169, s[44:45]
	v_cndmask_b32_e64 v86, v86, v169, s[42:43]
	v_cndmask_b32_e64 v85, v85, v169, s[40:41]
	v_cndmask_b32_e64 v84, v84, v169, s[38:39]
	v_cndmask_b32_e64 v83, v83, v169, s[36:37]
	v_cndmask_b32_e64 v82, v82, v169, s[34:35]
	v_cndmask_b32_e64 v81, v81, v169, s[30:31]
	v_cndmask_b32_e64 v79, v79, v169, s[28:29]
	v_cndmask_b32_e64 v78, v78, v169, s[26:27]
	v_cndmask_b32_e64 v77, v77, v169, s[24:25]
	v_cndmask_b32_e64 v76, v76, v169, s[22:23]
	v_cndmask_b32_e64 v75, v75, v169, s[20:21]
	v_cndmask_b32_e64 v74, v74, v169, s[18:19]
	v_cndmask_b32_e64 v73, v73, v169, s[16:17]
	v_cndmask_b32_e64 v72, v72, v169, s[14:15]
	v_cndmask_b32_e64 v71, v71, v169, s[12:13]
	v_cndmask_b32_e64 v70, v70, v169, s[10:11]
	v_cndmask_b32_e64 v69, v69, v169, s[8:9]
	v_cndmask_b32_e64 v68, v68, v169, s[6:7]
	v_cndmask_b32_e64 v67, v67, v169, s[4:5]
	v_cndmask_b32_e64 v66, v66, v169, s[2:3]
	v_cndmask_b32_e64 v65, v65, v169, s[0:1]
	v_cndmask_b32_e32 v64, v64, v169, vcc

.LBB0_1345:
	global_load_dwordx4 v[100:103], v164, s[0:1]
	global_load_dwordx4 v[104:107], v166, s[0:1]
	global_load_dwordx4 v[112:115], v164, s[2:3]
	global_load_dwordx4 v[108:111], v166, s[2:3]
